# MLA: next-K LDS stores moved from after barrier 1 into the PV MFMA stream, on top of QK-phase packing
# speedup vs baseline: 1.0131x; 1.0077x over previous
; DI void load_vtile(u32x4 (&rv)[4], const u16* __restrict__ vbase, int Lp, int key0, unsigned voffV) {
;   const char* ub = (const char*)vbase + (long)key0 * 2;
; #pragma unroll
;   for (int i = 0; i < 4; ++i) rv[i] = *(const u32x4*)(ub + (long)(32 * i) * Lp * 2 + voffV);
; }
; DI void mla_item(const Params& p, const GroupP& g, int item, char* smem, bool dry) {
;     ...
;   auto storeK = [&]() {
; #pragma unroll
;     for (int i = 0; i < 4; ++i) *(u32x4*)(sKn_st + i * 6400) = rk[i];
; #pragma unroll
;     for (int i = 0; i < 2; ++i) *(u32x4*)(sKr_st + i * 12800) = rk[4 + i];
;   };
;     ...
;     __syncthreads();
;     if (more) { storeK(); load_vtile(rv, vbase, Lp, (kt + 1) * 64, voffV); }
;     __builtin_amdgcn_sched_barrier(0);
.LBB0_156:
	v_cndmask_b32_e64 v184, 0, 1, s[4:5]
	v_cmp_ne_u32_e64 s[74:75], 1, v184
	s_andn2_b64 vcc, exec, s[4:5]
	s_barrier
	s_cbranch_vccnz .LBB0_158
	v_lshl_add_u64 v[152:153], v[194:195], 0, s[94:95]
	v_lshl_add_u64 v[164:165], v[152:153], 0, s[88:89]
	global_load_dwordx4 v[152:155], v[152:153], off
	s_nop 0
	global_load_dwordx4 v[156:159], v[164:165], off
	v_lshl_add_u64 v[164:165], v[164:165], 0, s[88:89]
	v_lshl_add_u64 v[168:169], v[164:165], 0, s[88:89]
	global_load_dwordx4 v[164:167], v[164:165], off
	s_nop 0
	global_load_dwordx4 v[168:171], v[168:169], off

; #define MFMA(a, b, c) __builtin_amdgcn_mfma_f32_32x32x16_bf16((a), (b), (c), 0, 0, 0)
; DI void softmax_pv(f32x16 (&sa)[2], f32x16 (&O)[4], float& m, float& l, const char* sV, int lr, int lh, bool first) {
;     ...
;   float rsum0 = 0.f, rsum1 = 0.f;
; #pragma unroll
;   for (int i = 0; i < 16; ++i) {
;     float p0 = __builtin_amdgcn_exp2f(sa[0][i]);
;     float p1 = __builtin_amdgcn_exp2f(sa[1][i]);
;     sa[0][i] = p0;
;     sa[1][i] = p1;
;     rsum0 += p0;
;     rsum1 += p1;
;   }
;   l += rsum0 + rsum1;
;   bf16x8 pf[4];
; #pragma unroll
;   for (int g4 = 0; g4 < 4; ++g4) {
;     const int kb = g4 >> 1, s2 = g4 & 1;
;     u32x4 pp;
; #pragma unroll
;     for (int j = 0; j < 4; ++j) pp[j] = pk2(sa[kb][8 * s2 + 2 * j], sa[kb][8 * s2 + 2 * j + 1]);
;     pf[g4] = __builtin_bit_cast(bf16x8, pp);
;   }
;   const char* vrd = sV + lr * 144 + lh * 16;
;   bf16x8 vfr[4];
; #pragma unroll
;   for (int t = 0; t < 3; ++t) vfr[t] = *(const bf16x8*)(vrd + (t & 3) * (32 * 144) + (t >> 2) * 32);
;   __builtin_amdgcn_sched_group_barrier(0x100, 3, 0);
; #pragma unroll
;   for (int t = 0; t < 16; ++t) {
;     if (t + 3 < 16) {
;       vfr[(t + 3) & 3] = *(const bf16x8*)(vrd + ((t + 3) & 3) * (32 * 144) + ((t + 3) >> 2) * 32);
;       __builtin_amdgcn_sched_group_barrier(0x100, 1, 0);
;     }
;     O[t & 3] = MFMA(vfr[t & 3], pf[t >> 2], O[t & 3]);
;     __builtin_amdgcn_sched_group_barrier(0x008, 1, 0);
;   }
; DI void mla_item(const Params& p, const GroupP& g, int item, char* smem, bool dry) {
;     ...
;   auto storeK = [&]() {
; #pragma unroll
;     for (int i = 0; i < 4; ++i) *(u32x4*)(sKn_st + i * 6400) = rk[i];
; #pragma unroll
;     for (int i = 0; i < 2; ++i) *(u32x4*)(sKr_st + i * 12800) = rk[4 + i];
;   };
.LBB0_160:
	ds_read_b128 v[202:205], v225 offset:25600
	ds_read_b128 v[232:235], v225 offset:30208
	ds_read_b128 v[236:239], v225 offset:34816
	ds_read_b128 v[240:243], v225 offset:39424
	v_exp_f32_e32 v80, v80
	v_exp_f32_e32 v81, v81
	v_exp_f32_e32 v82, v82
	v_exp_f32_e32 v83, v83
	v_exp_f32_e32 v84, v84
	v_exp_f32_e32 v85, v85
	v_exp_f32_e32 v86, v86
	v_exp_f32_e32 v87, v87
	v_cvt_pk_bf16_f32 v206, v80, v81
	v_cvt_pk_bf16_f32 v207, v82, v83
	v_cvt_pk_bf16_f32 v208, v84, v85
	v_cvt_pk_bf16_f32 v209, v86, v87
	v_exp_f32_e32 v231, v89
	v_exp_f32_e32 v184, v90
	s_waitcnt lgkmcnt(3)
	v_mfma_f32_32x32x16_bf16 v[48:63], v[202:205], v[206:209], v[48:63]
	ds_read_b128 v[202:205], v225 offset:25632
	v_exp_f32_e32 v90, v91
	v_exp_f32_e32 v89, v92
	v_exp_f32_e32 v92, v94
	v_exp_f32_e32 v91, v95
	v_exp_f32_e32 v95, v64
	v_exp_f32_e32 v94, v65
	s_waitcnt lgkmcnt(3)
	v_mfma_f32_32x32x16_bf16 v[32:47], v[232:235], v[206:209], v[32:47]
	ds_read_b128 v[244:247], v225 offset:30240
	v_exp_f32_e32 v232, v88
	v_exp_f32_e32 v88, v93
	v_exp_f32_e32 v93, v66
	v_exp_f32_e32 v66, v67
	v_exp_f32_e32 v65, v68
	v_exp_f32_e32 v64, v69
	s_waitcnt lgkmcnt(3)
	v_mfma_f32_32x32x16_bf16 v[16:31], v[236:239], v[206:209], v[16:31]
	ds_read_b128 v[234:237], v225 offset:34848
	v_exp_f32_e32 v68, v70
	v_exp_f32_e32 v67, v71
	v_exp_f32_e32 v233, v73
	v_exp_f32_e32 v71, v75
	v_exp_f32_e32 v70, v76
	v_exp_f32_e32 v69, v77
	s_waitcnt lgkmcnt(3)
	v_mfma_f32_32x32x16_bf16 v[0:15], v[240:243], v[206:209], v[0:15]
	ds_read_b128 v[238:241], v225 offset:39456
	s_waitcnt vmcnt(9)
	ds_write_b128 v191, v[144:147]
	s_waitcnt vmcnt(8)
	ds_write_b128 v191, v[148:151] offset:6400
	s_waitcnt vmcnt(7)
	ds_write_b128 v191, v[160:163] offset:12800
	v_cvt_pk_bf16_f32 v206, v232, v231
	v_cvt_pk_bf16_f32 v207, v184, v90
	v_cvt_pk_bf16_f32 v208, v89, v88
	v_cvt_pk_bf16_f32 v209, v92, v91
	v_exp_f32_e32 v73, v79
	s_and_b64 vcc, exec, s[74:75]
	s_waitcnt lgkmcnt(6)
	v_mfma_f32_32x32x16_bf16 v[48:63], v[202:205], v[206:209], v[48:63]
	ds_read_b128 v[202:205], v225 offset:25664
	s_waitcnt lgkmcnt(6)
	v_mfma_f32_32x32x16_bf16 v[32:47], v[244:247], v[206:209], v[32:47]
	ds_read_b128 v[242:245], v225 offset:30272
	s_waitcnt lgkmcnt(6)
	v_mfma_f32_32x32x16_bf16 v[16:31], v[234:237], v[206:209], v[16:31]
	ds_read_b128 v[234:237], v225 offset:34880
	s_waitcnt lgkmcnt(6)
	v_mfma_f32_32x32x16_bf16 v[0:15], v[238:241], v[206:209], v[0:15]
	ds_read_b128 v[238:241], v225 offset:39488
	s_waitcnt vmcnt(6)
	ds_write_b128 v191, v[172:175] offset:19200
	s_waitcnt vmcnt(5)
	ds_write_b128 v193, v[176:179] offset:256
	s_waitcnt vmcnt(4)
	ds_write_b128 v193, v[180:183] offset:13056
	v_cvt_pk_bf16_f32 v206, v95, v94
	v_cvt_pk_bf16_f32 v207, v93, v66
	v_cvt_pk_bf16_f32 v208, v65, v64
	v_cvt_pk_bf16_f32 v209, v68, v67
	s_waitcnt lgkmcnt(6)
	s_nop 0
	v_mfma_f32_32x32x16_bf16 v[48:63], v[202:205], v[206:209], v[48:63]
	ds_read_b128 v[202:205], v225 offset:25696
	s_waitcnt lgkmcnt(6)
	v_mfma_f32_32x32x16_bf16 v[32:47], v[242:245], v[206:209], v[32:47]
	ds_read_b128 v[242:245], v225 offset:30304
	s_waitcnt lgkmcnt(6)
	v_mfma_f32_32x32x16_bf16 v[16:31], v[234:237], v[206:209], v[16:31]
	ds_read_b128 v[246:249], v225 offset:34912
	v_exp_f32_e32 v234, v72
	v_exp_f32_e32 v72, v74
	v_exp_f32_e32 v74, v78
	v_cvt_pk_bf16_f32 v78, v70, v69
	v_cvt_pk_bf16_f32 v76, v234, v233
	v_cvt_pk_bf16_f32 v77, v72, v71
	s_waitcnt lgkmcnt(6)
	v_mfma_f32_32x32x16_bf16 v[0:15], v[238:241], v[206:209], v[0:15]
	ds_read_b128 v[206:209], v225 offset:39520
	v_cvt_pk_bf16_f32 v79, v74, v73
	s_waitcnt lgkmcnt(0)
	s_barrier
	v_mfma_f32_32x32x16_bf16 v[48:63], v[202:205], v[76:79], v[48:63]
	v_mfma_f32_32x32x16_bf16 v[32:47], v[242:245], v[76:79], v[32:47]
	v_mfma_f32_32x32x16_bf16 v[16:31], v[246:249], v[76:79], v[16:31]
	v_mfma_f32_32x32x16_bf16 v[0:15], v[206:209], v[76:79], v[0:15]
	s_branch .LBB0_151

; DI void load_vtile(u32x4 (&rv)[4], const u16* __restrict__ vbase, int Lp, int key0, unsigned voffV) {
;   const char* ub = (const char*)vbase + (long)key0 * 2;
; #pragma unroll
;   for (int i = 0; i < 4; ++i) rv[i] = *(const u32x4*)(ub + (long)(32 * i) * Lp * 2 + voffV);
; }
; DI void mla_item(const Params& p, const GroupP& g, int item, char* smem, bool dry) {
;     ...
;   auto storeK = [&]() {
; #pragma unroll
;     for (int i = 0; i < 4; ++i) *(u32x4*)(sKn_st + i * 6400) = rk[i];
; #pragma unroll
;     for (int i = 0; i < 2; ++i) *(u32x4*)(sKr_st + i * 12800) = rk[4 + i];
;   };
;     ...
;     __syncthreads();
;     if (more) { storeK(); load_vtile(rv, vbase, Lp, (kt + 1) * 64, voffV); }
;     __builtin_amdgcn_sched_barrier(0);
.LBB0_229:
	v_cndmask_b32_e64 v184, 0, 1, s[4:5]
	v_cmp_ne_u32_e64 s[74:75], 1, v184
	s_andn2_b64 vcc, exec, s[4:5]
	s_barrier
	s_cbranch_vccnz .LBB0_231
	v_lshl_add_u64 v[152:153], v[194:195], 0, s[94:95]
	v_lshl_add_u64 v[164:165], v[152:153], 0, s[96:97]
	global_load_dwordx4 v[152:155], v[152:153], off
	s_nop 0
	global_load_dwordx4 v[156:159], v[164:165], off
	v_lshl_add_u64 v[164:165], v[164:165], 0, s[96:97]
	v_lshl_add_u64 v[168:169], v[164:165], 0, s[96:97]
	global_load_dwordx4 v[164:167], v[164:165], off
	s_nop 0
	global_load_dwordx4 v[168:171], v[168:169], off

; #define MFMA(a, b, c) __builtin_amdgcn_mfma_f32_32x32x16_bf16((a), (b), (c), 0, 0, 0)
; DI void softmax_pv(f32x16 (&sa)[2], f32x16 (&O)[4], float& m, float& l, const char* sV, int lr, int lh, bool first) {
;     ...
;   float rsum0 = 0.f, rsum1 = 0.f;
; #pragma unroll
;   for (int i = 0; i < 16; ++i) {
;     float p0 = __builtin_amdgcn_exp2f(sa[0][i]);
;     float p1 = __builtin_amdgcn_exp2f(sa[1][i]);
;     sa[0][i] = p0;
;     sa[1][i] = p1;
;     rsum0 += p0;
;     rsum1 += p1;
;   }
;   l += rsum0 + rsum1;
;   bf16x8 pf[4];
; #pragma unroll
;   for (int g4 = 0; g4 < 4; ++g4) {
;     const int kb = g4 >> 1, s2 = g4 & 1;
;     u32x4 pp;
; #pragma unroll
;     for (int j = 0; j < 4; ++j) pp[j] = pk2(sa[kb][8 * s2 + 2 * j], sa[kb][8 * s2 + 2 * j + 1]);
;     pf[g4] = __builtin_bit_cast(bf16x8, pp);
;   }
;   const char* vrd = sV + lr * 144 + lh * 16;
;   bf16x8 vfr[4];
; #pragma unroll
;   for (int t = 0; t < 3; ++t) vfr[t] = *(const bf16x8*)(vrd + (t & 3) * (32 * 144) + (t >> 2) * 32);
;   __builtin_amdgcn_sched_group_barrier(0x100, 3, 0);
; #pragma unroll
;   for (int t = 0; t < 16; ++t) {
;     if (t + 3 < 16) {
;       vfr[(t + 3) & 3] = *(const bf16x8*)(vrd + ((t + 3) & 3) * (32 * 144) + ((t + 3) >> 2) * 32);
;       __builtin_amdgcn_sched_group_barrier(0x100, 1, 0);
;     }
;     O[t & 3] = MFMA(vfr[t & 3], pf[t >> 2], O[t & 3]);
;     __builtin_amdgcn_sched_group_barrier(0x008, 1, 0);
;   }
; DI void mla_item(const Params& p, const GroupP& g, int item, char* smem, bool dry) {
;     ...
;   auto storeK = [&]() {
; #pragma unroll
;     for (int i = 0; i < 4; ++i) *(u32x4*)(sKn_st + i * 6400) = rk[i];
; #pragma unroll
;     for (int i = 0; i < 2; ++i) *(u32x4*)(sKr_st + i * 12800) = rk[4 + i];
;   };
.LBB0_233:
	ds_read_b128 v[206:209], v225 offset:25600
	ds_read_b128 v[238:241], v225 offset:30208
	ds_read_b128 v[242:245], v225 offset:34816
	ds_read_b128 v[246:249], v225 offset:39424
	v_exp_f32_e32 v80, v80
	v_exp_f32_e32 v81, v81
	v_exp_f32_e32 v82, v82
	v_exp_f32_e32 v83, v83
	v_exp_f32_e32 v84, v84
	v_exp_f32_e32 v85, v85
	v_exp_f32_e32 v86, v86
	v_exp_f32_e32 v87, v87
	v_cvt_pk_bf16_f32 v234, v80, v81
	v_cvt_pk_bf16_f32 v235, v82, v83
	v_cvt_pk_bf16_f32 v236, v84, v85
	v_cvt_pk_bf16_f32 v237, v86, v87
	v_exp_f32_e32 v232, v88
	v_exp_f32_e32 v231, v89
	s_waitcnt lgkmcnt(3)
	v_mfma_f32_32x32x16_bf16 v[48:63], v[206:209], v[234:237], v[48:63]
	ds_read_b128 v[206:209], v225 offset:25632
	v_exp_f32_e32 v184, v90
	v_exp_f32_e32 v90, v91
	v_exp_f32_e32 v89, v92
	v_exp_f32_e32 v88, v93
	v_exp_f32_e32 v92, v94
	v_exp_f32_e32 v91, v95
	s_waitcnt lgkmcnt(3)
	v_mfma_f32_32x32x16_bf16 v[32:47], v[238:241], v[234:237], v[32:47]
	ds_read_b128 v[238:241], v225 offset:30240
	v_exp_f32_e32 v95, v64
	v_exp_f32_e32 v94, v65
	v_exp_f32_e32 v93, v66
	v_exp_f32_e32 v66, v67
	v_exp_f32_e32 v65, v68
	v_exp_f32_e32 v64, v69
	s_waitcnt lgkmcnt(3)
	v_mfma_f32_32x32x16_bf16 v[16:31], v[242:245], v[234:237], v[16:31]
	ds_read_b128 v[242:245], v225 offset:34848
	v_exp_f32_e32 v68, v70
	v_exp_f32_e32 v67, v71
	v_exp_f32_e32 v233, v73
	v_exp_f32_e32 v71, v75
	v_exp_f32_e32 v70, v76
	v_exp_f32_e32 v69, v77
	s_waitcnt lgkmcnt(3)
	v_mfma_f32_32x32x16_bf16 v[0:15], v[246:249], v[234:237], v[0:15]
	ds_read_b128 v[246:249], v225 offset:39456
	s_waitcnt vmcnt(9)
	ds_write_b128 v191, v[144:147]
	s_waitcnt vmcnt(8)
	ds_write_b128 v191, v[148:151] offset:6400
	s_waitcnt vmcnt(7)
	ds_write_b128 v191, v[160:163] offset:12800
	v_cvt_pk_bf16_f32 v234, v232, v231
	v_cvt_pk_bf16_f32 v235, v184, v90
	v_cvt_pk_bf16_f32 v236, v89, v88
	v_cvt_pk_bf16_f32 v237, v92, v91
	v_exp_f32_e32 v73, v79
	s_and_b64 vcc, exec, s[74:75]
	s_waitcnt lgkmcnt(6)
	v_mfma_f32_32x32x16_bf16 v[48:63], v[206:209], v[234:237], v[48:63]
	ds_read_b128 v[206:209], v225 offset:25664
	s_waitcnt lgkmcnt(6)
	v_mfma_f32_32x32x16_bf16 v[32:47], v[238:241], v[234:237], v[32:47]
	ds_read_b128 v[238:241], v225 offset:30272
	s_waitcnt lgkmcnt(6)
	v_mfma_f32_32x32x16_bf16 v[16:31], v[242:245], v[234:237], v[16:31]
	ds_read_b128 v[242:245], v225 offset:34880
	s_waitcnt lgkmcnt(6)
	v_mfma_f32_32x32x16_bf16 v[0:15], v[246:249], v[234:237], v[0:15]
	ds_read_b128 v[202:205], v225 offset:39488
	s_waitcnt vmcnt(6)
	ds_write_b128 v191, v[172:175] offset:19200
	s_waitcnt vmcnt(5)
	ds_write_b128 v193, v[176:179] offset:256
	s_waitcnt vmcnt(4)
	ds_write_b128 v193, v[180:183] offset:13056
	v_cvt_pk_bf16_f32 v246, v95, v94
	v_cvt_pk_bf16_f32 v247, v93, v66
	v_cvt_pk_bf16_f32 v248, v65, v64
	v_cvt_pk_bf16_f32 v249, v68, v67
	v_exp_f32_e32 v234, v72
	v_exp_f32_e32 v72, v74
	s_waitcnt lgkmcnt(6)
	v_mfma_f32_32x32x16_bf16 v[48:63], v[206:209], v[246:249], v[48:63]
	ds_read_b128 v[206:209], v225 offset:25696
	v_exp_f32_e32 v74, v78
	v_cvt_pk_bf16_f32 v76, v234, v233
	v_cvt_pk_bf16_f32 v77, v72, v71
	v_cvt_pk_bf16_f32 v78, v70, v69
	v_cvt_pk_bf16_f32 v79, v74, v73
	s_waitcnt lgkmcnt(6)
	v_mfma_f32_32x32x16_bf16 v[32:47], v[238:241], v[246:249], v[32:47]
	ds_read_b128 v[236:239], v225 offset:30304
	s_waitcnt lgkmcnt(6)
	v_mfma_f32_32x32x16_bf16 v[16:31], v[242:245], v[246:249], v[16:31]
	ds_read_b128 v[240:243], v225 offset:34912
	s_waitcnt lgkmcnt(6)
	v_mfma_f32_32x32x16_bf16 v[0:15], v[202:205], v[246:249], v[0:15]
	ds_read_b128 v[202:205], v225 offset:39520
	s_waitcnt lgkmcnt(0)
	s_barrier
	v_mfma_f32_32x32x16_bf16 v[48:63], v[206:209], v[76:79], v[48:63]
	v_mfma_f32_32x32x16_bf16 v[32:47], v[236:239], v[76:79], v[32:47]
	v_mfma_f32_32x32x16_bf16 v[16:31], v[240:243], v[76:79], v[16:31]
	v_mfma_f32_32x32x16_bf16 v[0:15], v[202:205], v[76:79], v[0:15]
	s_branch .LBB0_224
